# in-proj V tiles: transposed V^T written via per-wave LDS transpose + 16-byte global stores (was 128 two-byte stores per lane)
# baseline (speedup 1.0000x reference)
; __device__ __forceinline__ unsigned short f2bf1(float f) { unsigned u = __float_as_uint(f); return (unsigned short)((u + 0x7fffu + ((u >> 16) & 1u)) >> 16); }
;     __device__ __forceinline__ void operator()(const f32x4 (&acc)[2][2][4][2], const Unit& u, int wr, int wc, int fr, int fq) const {
;     ...
; #pragma unroll
;             for (int ai = 0; ai < 2; ++ai)
; #pragma unroll
;                 for (int m = 0; m < 4; ++m) {
;                     const int row = rowb + ai * HALF + m * 16, b = row >> 13, s = row & (SEQ_ - 1);
; #pragma unroll
;                     for (int bj = 0; bj < 2; ++bj) { const int h = (pn - 8) * 2 + bj;
; #pragma unroll
;                         for (int n = 0; n < 2; ++n)
; #pragma unroll
;                             for (int i = 0; i < 4; ++i) { const int e = jb + 4 * n + i; VT[((size_t)((b * 8 + h) * 128 + e)) * SEQ_ + s] = f2bf1(acc[ai][bj][m][n][i]); } }
;                 }
.LBB0_151:
	s_lshl_b32 s29, s61, 1
	s_ashr_i32 s31, s31, 10
	s_add_i32 s29, s29, -16
	s_and_b32 s31, s31, 0x1fffff8
	s_add_i32 s31, s31, s29
	v_and_b32_e32 v143, 0x1fcf, v142
	v_lshl_or_b32 v150, s31, 7, v148
	v_lshlrev_b32_e32 v146, 1, v143
	v_mov_b32_e32 v147, v32
	v_ashrrev_i32_e32 v151, 31, v150
	v_lshl_add_u64 v[146:147], s[24:25], 0, v[146:147]
	v_and_b32_e32 v162, 63, v228
	v_lshrrev_b32_e32 v163, 1, v162
	v_lshrrev_b32_e32 v164, 4, v162
	v_add_u32_e32 v166, v150, v163
	v_lshlrev_b32_e32 v165, 3, v164
	v_sub_u32_e32 v166, v166, v165
	v_mov_b32_e32 v167, 0
	v_lshlrev_b64 v[166:167], 14, v[166:167]
	v_and_b32_e32 v168, 1, v162
	v_lshlrev_b32_e32 v168, 4, v168
	v_and_b32_e32 v165, 15, v162
	v_lshlrev_b32_e32 v165, 1, v165
	v_sub_u32_e32 v168, v168, v165
	v_ashrrev_i32_e32 v169, 31, v168
	v_lshl_add_u64 v[170:171], v[146:147], 0, v[168:169]
	v_lshl_add_u64 v[170:171], v[170:171], 0, v[166:167]
	s_mov_b64 s[66:67], 0x200000
	v_lshl_add_u64 v[172:173], v[170:171], 0, s[66:67]
	v_lshrrev_b32_e32 v174, 6, v228
	v_mul_u32_u24_e32 v174, 0x480, v174
	v_add_u32_e32 v174, 0x20000, v174
	v_add_u32_e32 v175, v163, v164
	v_lshlrev_b32_e32 v175, 5, v175
	v_and_b32_e32 v176, 1, v162
	v_lshl_add_u32 v175, v176, 4, v175
	v_add_u32_e32 v175, v175, v174
	v_mul_u32_u24_e32 v176, 0x120, v164
	v_and_b32_e32 v177, 15, v162
	v_lshl_add_u32 v176, v177, 1, v176
	v_add_u32_e32 v174, v174, v176
	v_bfe_u32 v176, v126, 16, 1
	v_add3_u32 v176, v126, v176, s39
	v_bfe_u32 v177, v127, 16, 1
	v_add3_u32 v177, v127, v177, s39
	v_bfe_u32 v178, v128, 16, 1
	v_add3_u32 v178, v128, v178, s39
	v_bfe_u32 v179, v129, 16, 1
	v_add3_u32 v179, v129, v179, s39
	v_bfe_u32 v180, v122, 16, 1
	v_add3_u32 v180, v122, v180, s39
	v_bfe_u32 v181, v123, 16, 1
	v_add3_u32 v181, v123, v181, s39
	v_bfe_u32 v182, v124, 16, 1
	v_add3_u32 v182, v124, v182, s39
	v_bfe_u32 v183, v125, 16, 1
	v_add3_u32 v183, v125, v183, s39
	ds_write_b16_d16_hi v174, v176
	ds_write_b16_d16_hi v174, v177 offset:32
	ds_write_b16_d16_hi v174, v178 offset:64
	ds_write_b16_d16_hi v174, v179 offset:96
	ds_write_b16_d16_hi v174, v180 offset:128
	ds_write_b16_d16_hi v174, v181 offset:160
	ds_write_b16_d16_hi v174, v182 offset:192
	ds_write_b16_d16_hi v174, v183 offset:224
	ds_read_b128 v[184:187], v175
	v_bfe_u32 v176, v118, 16, 1
	v_add3_u32 v176, v118, v176, s39
	v_bfe_u32 v177, v119, 16, 1
	v_add3_u32 v177, v119, v177, s39
	v_bfe_u32 v178, v120, 16, 1
	v_add3_u32 v178, v120, v178, s39
	v_bfe_u32 v179, v121, 16, 1
	v_add3_u32 v179, v121, v179, s39
	v_bfe_u32 v180, v110, 16, 1
	v_add3_u32 v180, v110, v180, s39
	v_bfe_u32 v181, v111, 16, 1
	v_add3_u32 v181, v111, v181, s39
	v_bfe_u32 v182, v112, 16, 1
	v_add3_u32 v182, v112, v182, s39
	v_bfe_u32 v183, v113, 16, 1
	v_add3_u32 v183, v113, v183, s39
	ds_write_b16_d16_hi v174, v176
	ds_write_b16_d16_hi v174, v177 offset:32
	ds_write_b16_d16_hi v174, v178 offset:64
	ds_write_b16_d16_hi v174, v179 offset:96
	ds_write_b16_d16_hi v174, v180 offset:128
	ds_write_b16_d16_hi v174, v181 offset:160
	ds_write_b16_d16_hi v174, v182 offset:192
	ds_write_b16_d16_hi v174, v183 offset:224
	s_waitcnt lgkmcnt(8)
	global_store_dwordx4 v[170:171], v[184:187], off
	ds_read_b128 v[188:191], v175
	v_bfe_u32 v176, v114, 16, 1
	v_add3_u32 v176, v114, v176, s39
	v_bfe_u32 v177, v115, 16, 1
	v_add3_u32 v177, v115, v177, s39
	v_bfe_u32 v178, v116, 16, 1
	v_add3_u32 v178, v116, v178, s39
	v_bfe_u32 v179, v117, 16, 1
	v_add3_u32 v179, v117, v179, s39
	v_bfe_u32 v180, v106, 16, 1
	v_add3_u32 v180, v106, v180, s39
	v_bfe_u32 v181, v107, 16, 1
	v_add3_u32 v181, v107, v181, s39
	v_bfe_u32 v182, v108, 16, 1
	v_add3_u32 v182, v108, v182, s39
	v_bfe_u32 v183, v109, 16, 1
	v_add3_u32 v183, v109, v183, s39
	ds_write_b16_d16_hi v174, v176
	ds_write_b16_d16_hi v174, v177 offset:32
	ds_write_b16_d16_hi v174, v178 offset:64
	ds_write_b16_d16_hi v174, v179 offset:96
	ds_write_b16_d16_hi v174, v180 offset:128
	ds_write_b16_d16_hi v174, v181 offset:160
	ds_write_b16_d16_hi v174, v182 offset:192
	ds_write_b16_d16_hi v174, v183 offset:224
	s_waitcnt lgkmcnt(8)
	global_store_dwordx4 v[172:173], v[188:191], off
	ds_read_b128 v[184:187], v175
	v_bfe_u32 v176, v102, 16, 1
	v_add3_u32 v176, v102, v176, s39
	v_bfe_u32 v177, v103, 16, 1
	v_add3_u32 v177, v103, v177, s39
	v_bfe_u32 v178, v104, 16, 1
	v_add3_u32 v178, v104, v178, s39
	v_bfe_u32 v179, v105, 16, 1
	v_add3_u32 v179, v105, v179, s39
	v_bfe_u32 v180, v94, 16, 1
	v_add3_u32 v180, v94, v180, s39
	v_bfe_u32 v181, v95, 16, 1
	v_add3_u32 v181, v95, v181, s39
	v_bfe_u32 v182, v96, 16, 1
	v_add3_u32 v182, v96, v182, s39
	v_bfe_u32 v183, v97, 16, 1
	v_add3_u32 v183, v97, v183, s39
	ds_write_b16_d16_hi v174, v176
	ds_write_b16_d16_hi v174, v177 offset:32
	ds_write_b16_d16_hi v174, v178 offset:64
	ds_write_b16_d16_hi v174, v179 offset:96
	ds_write_b16_d16_hi v174, v180 offset:128
	ds_write_b16_d16_hi v174, v181 offset:160
	ds_write_b16_d16_hi v174, v182 offset:192
	ds_write_b16_d16_hi v174, v183 offset:224
	s_waitcnt lgkmcnt(8)
	global_store_dwordx4 v[170:171], v[184:187], off offset:32
	ds_read_b128 v[188:191], v175
	v_bfe_u32 v176, v98, 16, 1
	v_add3_u32 v176, v98, v176, s39
	v_bfe_u32 v177, v99, 16, 1
	v_add3_u32 v177, v99, v177, s39
	v_bfe_u32 v178, v100, 16, 1
	v_add3_u32 v178, v100, v178, s39
	v_bfe_u32 v179, v101, 16, 1
	v_add3_u32 v179, v101, v179, s39
	v_bfe_u32 v180, v90, 16, 1
	v_add3_u32 v180, v90, v180, s39
	v_bfe_u32 v181, v91, 16, 1
	v_add3_u32 v181, v91, v181, s39
	v_bfe_u32 v182, v92, 16, 1
	v_add3_u32 v182, v92, v182, s39
	v_bfe_u32 v183, v93, 16, 1
	v_add3_u32 v183, v93, v183, s39
	ds_write_b16_d16_hi v174, v176
	ds_write_b16_d16_hi v174, v177 offset:32
	ds_write_b16_d16_hi v174, v178 offset:64
	ds_write_b16_d16_hi v174, v179 offset:96
	ds_write_b16_d16_hi v174, v180 offset:128
	ds_write_b16_d16_hi v174, v181 offset:160
	ds_write_b16_d16_hi v174, v182 offset:192
	ds_write_b16_d16_hi v174, v183 offset:224
	s_waitcnt lgkmcnt(8)
; __device__ __forceinline__ unsigned short f2bf1(float f) { unsigned u = __float_as_uint(f); return (unsigned short)((u + 0x7fffu + ((u >> 16) & 1u)) >> 16); }
;     __device__ __forceinline__ void operator()(const f32x4 (&acc)[2][2][4][2], const Unit& u, int wr, int wc, int fr, int fq) const {
;     ...
; #pragma unroll
;             for (int ai = 0; ai < 2; ++ai)
; #pragma unroll
;                 for (int m = 0; m < 4; ++m) {
;                     const int row = rowb + ai * HALF + m * 16, b = row >> 13, s = row & (SEQ_ - 1);
; #pragma unroll
;                     for (int bj = 0; bj < 2; ++bj) { const int h = (pn - 8) * 2 + bj;
; #pragma unroll
;                         for (int n = 0; n < 2; ++n)
; #pragma unroll
;                             for (int i = 0; i < 4; ++i) { const int e = jb + 4 * n + i; VT[((size_t)((b * 8 + h) * 128 + e)) * SEQ_ + s] = f2bf1(acc[ai][bj][m][n][i]); } }
;                 }
	global_store_dwordx4 v[172:173], v[188:191], off offset:32
	ds_read_b128 v[184:187], v175
	v_bfe_u32 v176, v86, 16, 1
	v_add3_u32 v176, v86, v176, s39
	v_bfe_u32 v177, v87, 16, 1
	v_add3_u32 v177, v87, v177, s39
	v_bfe_u32 v178, v88, 16, 1
	v_add3_u32 v178, v88, v178, s39
	v_bfe_u32 v179, v89, 16, 1
	v_add3_u32 v179, v89, v179, s39
	v_bfe_u32 v180, v78, 16, 1
	v_add3_u32 v180, v78, v180, s39
	v_bfe_u32 v181, v79, 16, 1
	v_add3_u32 v181, v79, v181, s39
	v_bfe_u32 v182, v80, 16, 1
	v_add3_u32 v182, v80, v182, s39
	v_bfe_u32 v183, v81, 16, 1
	v_add3_u32 v183, v81, v183, s39
	ds_write_b16_d16_hi v174, v176
	ds_write_b16_d16_hi v174, v177 offset:32
	ds_write_b16_d16_hi v174, v178 offset:64
	ds_write_b16_d16_hi v174, v179 offset:96
	ds_write_b16_d16_hi v174, v180 offset:128
	ds_write_b16_d16_hi v174, v181 offset:160
	ds_write_b16_d16_hi v174, v182 offset:192
	ds_write_b16_d16_hi v174, v183 offset:224
	s_waitcnt lgkmcnt(8)
	global_store_dwordx4 v[170:171], v[184:187], off offset:64
	ds_read_b128 v[188:191], v175
	v_bfe_u32 v176, v82, 16, 1
	v_add3_u32 v176, v82, v176, s39
	v_bfe_u32 v177, v83, 16, 1
	v_add3_u32 v177, v83, v177, s39
	v_bfe_u32 v178, v84, 16, 1
	v_add3_u32 v178, v84, v178, s39
	v_bfe_u32 v179, v85, 16, 1
	v_add3_u32 v179, v85, v179, s39
	v_bfe_u32 v180, v74, 16, 1
	v_add3_u32 v180, v74, v180, s39
	v_bfe_u32 v181, v75, 16, 1
	v_add3_u32 v181, v75, v181, s39
	v_bfe_u32 v182, v76, 16, 1
	v_add3_u32 v182, v76, v182, s39
	v_bfe_u32 v183, v77, 16, 1
	v_add3_u32 v183, v77, v183, s39
	ds_write_b16_d16_hi v174, v176
	ds_write_b16_d16_hi v174, v177 offset:32
	ds_write_b16_d16_hi v174, v178 offset:64
	ds_write_b16_d16_hi v174, v179 offset:96
	ds_write_b16_d16_hi v174, v180 offset:128
	ds_write_b16_d16_hi v174, v181 offset:160
	ds_write_b16_d16_hi v174, v182 offset:192
	ds_write_b16_d16_hi v174, v183 offset:224
	s_waitcnt lgkmcnt(8)
	global_store_dwordx4 v[172:173], v[188:191], off offset:64
	ds_read_b128 v[184:187], v175
	v_bfe_u32 v176, v70, 16, 1
	v_add3_u32 v176, v70, v176, s39
	v_bfe_u32 v177, v71, 16, 1
	v_add3_u32 v177, v71, v177, s39
	v_bfe_u32 v178, v72, 16, 1
	v_add3_u32 v178, v72, v178, s39
	v_bfe_u32 v179, v73, 16, 1
	v_add3_u32 v179, v73, v179, s39
	v_bfe_u32 v180, v66, 16, 1
	v_add3_u32 v180, v66, v180, s39
	v_bfe_u32 v181, v67, 16, 1
	v_add3_u32 v181, v67, v181, s39
	v_bfe_u32 v182, v68, 16, 1
	v_add3_u32 v182, v68, v182, s39
	v_bfe_u32 v183, v69, 16, 1
	v_add3_u32 v183, v69, v183, s39
	ds_write_b16_d16_hi v174, v176
	ds_write_b16_d16_hi v174, v177 offset:32
	ds_write_b16_d16_hi v174, v178 offset:64
	ds_write_b16_d16_hi v174, v179 offset:96
	ds_write_b16_d16_hi v174, v180 offset:128
	ds_write_b16_d16_hi v174, v181 offset:160
	ds_write_b16_d16_hi v174, v182 offset:192
	ds_write_b16_d16_hi v174, v183 offset:224
	s_waitcnt lgkmcnt(8)
	global_store_dwordx4 v[170:171], v[184:187], off offset:96
	ds_read_b128 v[188:191], v175
	v_bfe_u32 v176, v62, 16, 1
	v_add3_u32 v176, v62, v176, s39
	v_bfe_u32 v177, v63, 16, 1
	v_add3_u32 v177, v63, v177, s39
	v_bfe_u32 v178, v64, 16, 1
	v_add3_u32 v178, v64, v178, s39
	v_bfe_u32 v179, v65, 16, 1
	v_add3_u32 v179, v65, v179, s39
	v_bfe_u32 v180, v58, 16, 1
	v_add3_u32 v180, v58, v180, s39
	v_bfe_u32 v181, v59, 16, 1
	v_add3_u32 v181, v59, v181, s39
	v_bfe_u32 v182, v60, 16, 1
	v_add3_u32 v182, v60, v182, s39
	v_bfe_u32 v183, v61, 16, 1
	v_add3_u32 v183, v61, v183, s39
	ds_write_b16_d16_hi v174, v176
	ds_write_b16_d16_hi v174, v177 offset:32
	ds_write_b16_d16_hi v174, v178 offset:64
	ds_write_b16_d16_hi v174, v179 offset:96
	ds_write_b16_d16_hi v174, v180 offset:128
	ds_write_b16_d16_hi v174, v181 offset:160
	ds_write_b16_d16_hi v174, v182 offset:192
	ds_write_b16_d16_hi v174, v183 offset:224
	s_waitcnt lgkmcnt(8)
	global_store_dwordx4 v[172:173], v[188:191], off offset:96
	ds_read_b128 v[184:187], v175
	v_bfe_u32 v176, v54, 16, 1
	v_add3_u32 v176, v54, v176, s39
	v_bfe_u32 v177, v55, 16, 1
	v_add3_u32 v177, v55, v177, s39
	v_bfe_u32 v178, v56, 16, 1
	v_add3_u32 v178, v56, v178, s39
	v_bfe_u32 v179, v57, 16, 1
	v_add3_u32 v179, v57, v179, s39
	v_bfe_u32 v180, v46, 16, 1
	v_add3_u32 v180, v46, v180, s39
	v_bfe_u32 v181, v47, 16, 1
	v_add3_u32 v181, v47, v181, s39
	v_bfe_u32 v182, v48, 16, 1
	v_add3_u32 v182, v48, v182, s39
	v_bfe_u32 v183, v49, 16, 1
	v_add3_u32 v183, v49, v183, s39
	ds_write_b16_d16_hi v174, v176
	ds_write_b16_d16_hi v174, v177 offset:32
	ds_write_b16_d16_hi v174, v178 offset:64
	ds_write_b16_d16_hi v174, v179 offset:96
	ds_write_b16_d16_hi v174, v180 offset:128
	ds_write_b16_d16_hi v174, v181 offset:160
	ds_write_b16_d16_hi v174, v182 offset:192
	ds_write_b16_d16_hi v174, v183 offset:224
	s_waitcnt lgkmcnt(8)
	global_store_dwordx4 v[170:171], v[184:187], off offset:256
	ds_read_b128 v[188:191], v175
	v_bfe_u32 v176, v50, 16, 1
	v_add3_u32 v176, v50, v176, s39
	v_bfe_u32 v177, v51, 16, 1
	v_add3_u32 v177, v51, v177, s39
	v_bfe_u32 v178, v52, 16, 1
	v_add3_u32 v178, v52, v178, s39
	v_bfe_u32 v179, v53, 16, 1
	v_add3_u32 v179, v53, v179, s39
	v_bfe_u32 v180, v42, 16, 1
	v_add3_u32 v180, v42, v180, s39
	v_bfe_u32 v181, v43, 16, 1
	v_add3_u32 v181, v43, v181, s39
	v_bfe_u32 v182, v44, 16, 1
	v_add3_u32 v182, v44, v182, s39
	v_bfe_u32 v183, v45, 16, 1
	v_add3_u32 v183, v45, v183, s39
	ds_write_b16_d16_hi v174, v176
	ds_write_b16_d16_hi v174, v177 offset:32
	ds_write_b16_d16_hi v174, v178 offset:64
	ds_write_b16_d16_hi v174, v179 offset:96
	ds_write_b16_d16_hi v174, v180 offset:128
	ds_write_b16_d16_hi v174, v181 offset:160
	ds_write_b16_d16_hi v174, v182 offset:192
	ds_write_b16_d16_hi v174, v183 offset:224
	s_waitcnt lgkmcnt(8)
; __device__ __forceinline__ unsigned short f2bf1(float f) { unsigned u = __float_as_uint(f); return (unsigned short)((u + 0x7fffu + ((u >> 16) & 1u)) >> 16); }
;     __device__ __forceinline__ void operator()(const f32x4 (&acc)[2][2][4][2], const Unit& u, int wr, int wc, int fr, int fq) const {
;     ...
; #pragma unroll
;             for (int ai = 0; ai < 2; ++ai)
; #pragma unroll
;                 for (int m = 0; m < 4; ++m) {
;                     const int row = rowb + ai * HALF + m * 16, b = row >> 13, s = row & (SEQ_ - 1);
; #pragma unroll
;                     for (int bj = 0; bj < 2; ++bj) { const int h = (pn - 8) * 2 + bj;
; #pragma unroll
;                         for (int n = 0; n < 2; ++n)
; #pragma unroll
;                             for (int i = 0; i < 4; ++i) { const int e = jb + 4 * n + i; VT[((size_t)((b * 8 + h) * 128 + e)) * SEQ_ + s] = f2bf1(acc[ai][bj][m][n][i]); } }
;                 }
	global_store_dwordx4 v[172:173], v[188:191], off offset:256
	ds_read_b128 v[184:187], v175
	v_bfe_u32 v176, v38, 16, 1
	v_add3_u32 v176, v38, v176, s39
	v_bfe_u32 v177, v39, 16, 1
	v_add3_u32 v177, v39, v177, s39
	v_bfe_u32 v178, v40, 16, 1
	v_add3_u32 v178, v40, v178, s39
	v_bfe_u32 v179, v41, 16, 1
	v_add3_u32 v179, v41, v179, s39
	v_bfe_u32 v180, v28, 16, 1
	v_add3_u32 v180, v28, v180, s39
	v_bfe_u32 v181, v29, 16, 1
	v_add3_u32 v181, v29, v181, s39
	v_bfe_u32 v182, v30, 16, 1
	v_add3_u32 v182, v30, v182, s39
	v_bfe_u32 v183, v31, 16, 1
	v_add3_u32 v183, v31, v183, s39
	ds_write_b16_d16_hi v174, v176
	ds_write_b16_d16_hi v174, v177 offset:32
	ds_write_b16_d16_hi v174, v178 offset:64
	ds_write_b16_d16_hi v174, v179 offset:96
	ds_write_b16_d16_hi v174, v180 offset:128
	ds_write_b16_d16_hi v174, v181 offset:160
	ds_write_b16_d16_hi v174, v182 offset:192
	ds_write_b16_d16_hi v174, v183 offset:224
	s_waitcnt lgkmcnt(8)
	global_store_dwordx4 v[170:171], v[184:187], off offset:288
	ds_read_b128 v[188:191], v175
	v_bfe_u32 v176, v34, 16, 1
	v_add3_u32 v176, v34, v176, s39
	v_bfe_u32 v177, v35, 16, 1
	v_add3_u32 v177, v35, v177, s39
	v_bfe_u32 v178, v36, 16, 1
	v_add3_u32 v178, v36, v178, s39
	v_bfe_u32 v179, v37, 16, 1
	v_add3_u32 v179, v37, v179, s39
	v_bfe_u32 v180, v24, 16, 1
	v_add3_u32 v180, v24, v180, s39
	v_bfe_u32 v181, v25, 16, 1
	v_add3_u32 v181, v25, v181, s39
	v_bfe_u32 v182, v26, 16, 1
	v_add3_u32 v182, v26, v182, s39
	v_bfe_u32 v183, v27, 16, 1
	v_add3_u32 v183, v27, v183, s39
	ds_write_b16_d16_hi v174, v176
	ds_write_b16_d16_hi v174, v177 offset:32
	ds_write_b16_d16_hi v174, v178 offset:64
	ds_write_b16_d16_hi v174, v179 offset:96
	ds_write_b16_d16_hi v174, v180 offset:128
	ds_write_b16_d16_hi v174, v181 offset:160
	ds_write_b16_d16_hi v174, v182 offset:192
	ds_write_b16_d16_hi v174, v183 offset:224
	s_waitcnt lgkmcnt(8)
	global_store_dwordx4 v[172:173], v[188:191], off offset:288
	ds_read_b128 v[184:187], v175
	v_bfe_u32 v176, v20, 16, 1
	v_add3_u32 v176, v20, v176, s39
	v_bfe_u32 v177, v21, 16, 1
	v_add3_u32 v177, v21, v177, s39
	v_bfe_u32 v178, v22, 16, 1
	v_add3_u32 v178, v22, v178, s39
	v_bfe_u32 v179, v23, 16, 1
	v_add3_u32 v179, v23, v179, s39
	v_bfe_u32 v180, v12, 16, 1
	v_add3_u32 v180, v12, v180, s39
	v_bfe_u32 v181, v13, 16, 1
	v_add3_u32 v181, v13, v181, s39
	v_bfe_u32 v182, v14, 16, 1
	v_add3_u32 v182, v14, v182, s39
	v_bfe_u32 v183, v15, 16, 1
	v_add3_u32 v183, v15, v183, s39
	ds_write_b16_d16_hi v174, v176
	ds_write_b16_d16_hi v174, v177 offset:32
	ds_write_b16_d16_hi v174, v178 offset:64
	ds_write_b16_d16_hi v174, v179 offset:96
	ds_write_b16_d16_hi v174, v180 offset:128
	ds_write_b16_d16_hi v174, v181 offset:160
	ds_write_b16_d16_hi v174, v182 offset:192
	ds_write_b16_d16_hi v174, v183 offset:224
	s_waitcnt lgkmcnt(8)
	global_store_dwordx4 v[170:171], v[184:187], off offset:320
	ds_read_b128 v[188:191], v175
	v_bfe_u32 v176, v16, 16, 1
	v_add3_u32 v176, v16, v176, s39
	v_bfe_u32 v177, v17, 16, 1
	v_add3_u32 v177, v17, v177, s39
	v_bfe_u32 v178, v18, 16, 1
	v_add3_u32 v178, v18, v178, s39
	v_bfe_u32 v179, v19, 16, 1
	v_add3_u32 v179, v19, v179, s39
	v_bfe_u32 v180, v8, 16, 1
	v_add3_u32 v180, v8, v180, s39
	v_bfe_u32 v181, v9, 16, 1
	v_add3_u32 v181, v9, v181, s39
	v_bfe_u32 v182, v10, 16, 1
	v_add3_u32 v182, v10, v182, s39
	v_bfe_u32 v183, v11, 16, 1
	v_add3_u32 v183, v11, v183, s39
	ds_write_b16_d16_hi v174, v176
	ds_write_b16_d16_hi v174, v177 offset:32
	ds_write_b16_d16_hi v174, v178 offset:64
	ds_write_b16_d16_hi v174, v179 offset:96
	ds_write_b16_d16_hi v174, v180 offset:128
	ds_write_b16_d16_hi v174, v181 offset:160
	ds_write_b16_d16_hi v174, v182 offset:192
	ds_write_b16_d16_hi v174, v183 offset:224
	s_waitcnt lgkmcnt(8)
	global_store_dwordx4 v[172:173], v[188:191], off offset:320
	ds_read_b128 v[184:187], v175
	v_bfe_u32 v176, v4, 16, 1
	v_add3_u32 v176, v4, v176, s39
	v_bfe_u32 v177, v5, 16, 1
	v_add3_u32 v177, v5, v177, s39
	v_bfe_u32 v178, v6, 16, 1
	v_add3_u32 v178, v6, v178, s39
	v_bfe_u32 v179, v7, 16, 1
	v_add3_u32 v179, v7, v179, s39
	v_bfe_u32 v180, v0, 16, 1
	v_add3_u32 v180, v0, v180, s39
	v_bfe_u32 v181, v1, 16, 1
	v_add3_u32 v181, v1, v181, s39
	v_bfe_u32 v182, v2, 16, 1
	v_add3_u32 v182, v2, v182, s39
	v_bfe_u32 v183, v3, 16, 1
	v_add3_u32 v183, v3, v183, s39
	ds_write_b16_d16_hi v174, v176
	ds_write_b16_d16_hi v174, v177 offset:32
	ds_write_b16_d16_hi v174, v178 offset:64
	ds_write_b16_d16_hi v174, v179 offset:96
	ds_write_b16_d16_hi v174, v180 offset:128
	ds_write_b16_d16_hi v174, v181 offset:160
	ds_write_b16_d16_hi v174, v182 offset:192
	ds_write_b16_d16_hi v174, v183 offset:224
	s_waitcnt lgkmcnt(8)
	global_store_dwordx4 v[170:171], v[184:187], off offset:352
	ds_read_b128 v[188:191], v175
	s_waitcnt lgkmcnt(0)
	global_store_dwordx4 v[172:173], v[188:191], off offset:352
	s_cbranch_execnz .LBB0_150

; __device__ __forceinline__ unsigned short f2bf1(float f) { unsigned u = __float_as_uint(f); return (unsigned short)((u + 0x7fffu + ((u >> 16) & 1u)) >> 16); }
;     __device__ __forceinline__ void operator()(const f32x4 (&acc)[2][2][4][2], const Unit& u, int wr, int wc, int fr, int fq) const {
;     ...
;             const int h = (pn - 8) >> 1, eb = ((pn - 8) & 1) * 256 + jb;
; #pragma unroll
;             for (int ai = 0; ai < 2; ++ai)
; #pragma unroll
;                 for (int m = 0; m < 4; ++m) {
;                     const int row = rowb + ai * HALF + m * 16, b = row >> 13, s = row & (SEQ_ - 1);
; #pragma unroll
;                     for (int bj = 0; bj < 2; ++bj)
; #pragma unroll
;                         for (int n = 0; n < 2; ++n)
; #pragma unroll
;                             for (int i = 0; i < 4; ++i) { const int e = eb + 128 * bj + 4 * n + i; VT[((size_t)((b * 4 + h) * 512 + e)) * SEQ_ + s] = f2bf1(acc[ai][bj][m][n][i]); }
;                 }
.LBB0_557:
	s_andn2_b64 vcc, exec, s[34:35]
	s_cbranch_vccnz .LBB0_559
	s_add_i32 s34, s61, -8
	s_ashr_i32 s37, s36, 11
	s_lshr_b32 s34, s34, 1
	s_and_b32 s37, s37, 0x7ffffc
	s_lshl_b32 s35, s61, 8
	s_add_i32 s37, s37, s34
	s_and_b32 s35, s35, 0x100
	s_lshl_b32 s37, s37, 9
	s_or_b32 s37, s37, s35
	v_and_b32_e32 v145, 0x1fcf, v144
	v_or_b32_e32 v146, s37, v151
	v_lshlrev_b32_e32 v148, 1, v145
	v_mov_b32_e32 v149, v32
	v_ashrrev_i32_e32 v147, 31, v146
	v_lshl_add_u64 v[148:149], s[26:27], 0, v[148:149]
	v_and_b32_e32 v162, 63, v228
	v_lshrrev_b32_e32 v163, 1, v162
	v_lshrrev_b32_e32 v164, 4, v162
	v_add_u32_e32 v166, v146, v163
	v_lshlrev_b32_e32 v165, 3, v164
	v_sub_u32_e32 v166, v166, v165
	v_mov_b32_e32 v167, 0
	v_lshlrev_b64 v[166:167], 14, v[166:167]
	v_and_b32_e32 v168, 1, v162
	v_lshlrev_b32_e32 v168, 4, v168
	v_and_b32_e32 v165, 15, v162
	v_lshlrev_b32_e32 v165, 1, v165
	v_sub_u32_e32 v168, v168, v165
	v_ashrrev_i32_e32 v169, 31, v168
	v_lshl_add_u64 v[170:171], v[148:149], 0, v[168:169]
	v_lshl_add_u64 v[170:171], v[170:171], 0, v[166:167]
	s_mov_b64 s[66:67], 0x200000
	v_lshl_add_u64 v[172:173], v[170:171], 0, s[66:67]
	v_lshrrev_b32_e32 v174, 6, v228
	v_mul_u32_u24_e32 v174, 0x480, v174
	v_add_u32_e32 v174, 0x20000, v174
	v_add_u32_e32 v175, v163, v164
	v_lshlrev_b32_e32 v175, 5, v175
	v_and_b32_e32 v176, 1, v162
	v_lshl_add_u32 v175, v176, 4, v175
	v_add_u32_e32 v175, v175, v174
	v_mul_u32_u24_e32 v176, 0x120, v164
	v_and_b32_e32 v177, 15, v162
	v_lshl_add_u32 v176, v177, 1, v176
	v_add_u32_e32 v174, v174, v176
	v_bfe_u32 v176, v126, 16, 1
	v_add3_u32 v176, v126, v176, s39
	v_bfe_u32 v177, v127, 16, 1
	v_add3_u32 v177, v127, v177, s39
	v_bfe_u32 v178, v128, 16, 1
	v_add3_u32 v178, v128, v178, s39
	v_bfe_u32 v179, v129, 16, 1
	v_add3_u32 v179, v129, v179, s39
	v_bfe_u32 v180, v118, 16, 1
	v_add3_u32 v180, v118, v180, s39
	v_bfe_u32 v181, v119, 16, 1
	v_add3_u32 v181, v119, v181, s39
	v_bfe_u32 v182, v120, 16, 1
	v_add3_u32 v182, v120, v182, s39
	v_bfe_u32 v183, v121, 16, 1
	v_add3_u32 v183, v121, v183, s39
	ds_write_b16_d16_hi v174, v176
	ds_write_b16_d16_hi v174, v177 offset:32
	ds_write_b16_d16_hi v174, v178 offset:64
	ds_write_b16_d16_hi v174, v179 offset:96
	ds_write_b16_d16_hi v174, v180 offset:128
	ds_write_b16_d16_hi v174, v181 offset:160
	ds_write_b16_d16_hi v174, v182 offset:192
	ds_write_b16_d16_hi v174, v183 offset:224
	ds_read_b128 v[184:187], v175
	v_bfe_u32 v176, v122, 16, 1
	v_add3_u32 v176, v122, v176, s39
	v_bfe_u32 v177, v123, 16, 1
	v_add3_u32 v177, v123, v177, s39
	v_bfe_u32 v178, v124, 16, 1
	v_add3_u32 v178, v124, v178, s39
	v_bfe_u32 v179, v125, 16, 1
	v_add3_u32 v179, v125, v179, s39
	v_bfe_u32 v180, v114, 16, 1
	v_add3_u32 v180, v114, v180, s39
	v_bfe_u32 v181, v115, 16, 1
	v_add3_u32 v181, v115, v181, s39
	v_bfe_u32 v182, v116, 16, 1
	v_add3_u32 v182, v116, v182, s39
	v_bfe_u32 v183, v117, 16, 1
	v_add3_u32 v183, v117, v183, s39
	ds_write_b16_d16_hi v174, v176
	ds_write_b16_d16_hi v174, v177 offset:32
	ds_write_b16_d16_hi v174, v178 offset:64
	ds_write_b16_d16_hi v174, v179 offset:96
	ds_write_b16_d16_hi v174, v180 offset:128
	ds_write_b16_d16_hi v174, v181 offset:160
	ds_write_b16_d16_hi v174, v182 offset:192
	ds_write_b16_d16_hi v174, v183 offset:224
	s_waitcnt lgkmcnt(8)
	global_store_dwordx4 v[170:171], v[184:187], off
	ds_read_b128 v[188:191], v175
	v_bfe_u32 v176, v110, 16, 1
	v_add3_u32 v176, v110, v176, s39
	v_bfe_u32 v177, v111, 16, 1
	v_add3_u32 v177, v111, v177, s39
	v_bfe_u32 v178, v112, 16, 1
	v_add3_u32 v178, v112, v178, s39
	v_bfe_u32 v179, v113, 16, 1
	v_add3_u32 v179, v113, v179, s39
	v_bfe_u32 v180, v102, 16, 1
	v_add3_u32 v180, v102, v180, s39
	v_bfe_u32 v181, v103, 16, 1
	v_add3_u32 v181, v103, v181, s39
	v_bfe_u32 v182, v104, 16, 1
	v_add3_u32 v182, v104, v182, s39
	v_bfe_u32 v183, v105, 16, 1
	v_add3_u32 v183, v105, v183, s39
	ds_write_b16_d16_hi v174, v176
	ds_write_b16_d16_hi v174, v177 offset:32
	ds_write_b16_d16_hi v174, v178 offset:64
	ds_write_b16_d16_hi v174, v179 offset:96
	ds_write_b16_d16_hi v174, v180 offset:128
	ds_write_b16_d16_hi v174, v181 offset:160
	ds_write_b16_d16_hi v174, v182 offset:192
	ds_write_b16_d16_hi v174, v183 offset:224
	s_waitcnt lgkmcnt(8)
	global_store_dwordx4 v[172:173], v[188:191], off
	ds_read_b128 v[184:187], v175
	v_bfe_u32 v176, v106, 16, 1
	v_add3_u32 v176, v106, v176, s39
	v_bfe_u32 v177, v107, 16, 1
	v_add3_u32 v177, v107, v177, s39
	v_bfe_u32 v178, v108, 16, 1
	v_add3_u32 v178, v108, v178, s39
	v_bfe_u32 v179, v109, 16, 1
	v_add3_u32 v179, v109, v179, s39
	v_bfe_u32 v180, v98, 16, 1
	v_add3_u32 v180, v98, v180, s39
	v_bfe_u32 v181, v99, 16, 1
	v_add3_u32 v181, v99, v181, s39
	v_bfe_u32 v182, v100, 16, 1
	v_add3_u32 v182, v100, v182, s39
	v_bfe_u32 v183, v101, 16, 1
	v_add3_u32 v183, v101, v183, s39
	ds_write_b16_d16_hi v174, v176
	ds_write_b16_d16_hi v174, v177 offset:32
	ds_write_b16_d16_hi v174, v178 offset:64
	ds_write_b16_d16_hi v174, v179 offset:96
	ds_write_b16_d16_hi v174, v180 offset:128
	ds_write_b16_d16_hi v174, v181 offset:160
	ds_write_b16_d16_hi v174, v182 offset:192
	ds_write_b16_d16_hi v174, v183 offset:224
	s_waitcnt lgkmcnt(8)
	global_store_dwordx4 v[170:171], v[184:187], off offset:32
	ds_read_b128 v[188:191], v175
	v_bfe_u32 v176, v94, 16, 1
	v_add3_u32 v176, v94, v176, s39
	v_bfe_u32 v177, v95, 16, 1
	v_add3_u32 v177, v95, v177, s39
	v_bfe_u32 v178, v96, 16, 1
	v_add3_u32 v178, v96, v178, s39
	v_bfe_u32 v179, v97, 16, 1
	v_add3_u32 v179, v97, v179, s39
	v_bfe_u32 v180, v86, 16, 1
	v_add3_u32 v180, v86, v180, s39
	v_bfe_u32 v181, v87, 16, 1
	v_add3_u32 v181, v87, v181, s39
	v_bfe_u32 v182, v88, 16, 1
	v_add3_u32 v182, v88, v182, s39
	v_bfe_u32 v183, v89, 16, 1
	v_add3_u32 v183, v89, v183, s39
	ds_write_b16_d16_hi v174, v176
	ds_write_b16_d16_hi v174, v177 offset:32
	ds_write_b16_d16_hi v174, v178 offset:64
	ds_write_b16_d16_hi v174, v179 offset:96
	ds_write_b16_d16_hi v174, v180 offset:128
	ds_write_b16_d16_hi v174, v181 offset:160
	ds_write_b16_d16_hi v174, v182 offset:192
	ds_write_b16_d16_hi v174, v183 offset:224
	s_waitcnt lgkmcnt(8)
; __device__ __forceinline__ unsigned short f2bf1(float f) { unsigned u = __float_as_uint(f); return (unsigned short)((u + 0x7fffu + ((u >> 16) & 1u)) >> 16); }
;     __device__ __forceinline__ void operator()(const f32x4 (&acc)[2][2][4][2], const Unit& u, int wr, int wc, int fr, int fq) const {
;     ...
;             const int h = (pn - 8) >> 1, eb = ((pn - 8) & 1) * 256 + jb;
; #pragma unroll
;             for (int ai = 0; ai < 2; ++ai)
; #pragma unroll
;                 for (int m = 0; m < 4; ++m) {
;                     const int row = rowb + ai * HALF + m * 16, b = row >> 13, s = row & (SEQ_ - 1);
; #pragma unroll
;                     for (int bj = 0; bj < 2; ++bj)
; #pragma unroll
;                         for (int n = 0; n < 2; ++n)
; #pragma unroll
;                             for (int i = 0; i < 4; ++i) { const int e = eb + 128 * bj + 4 * n + i; VT[((size_t)((b * 4 + h) * 512 + e)) * SEQ_ + s] = f2bf1(acc[ai][bj][m][n][i]); }
;                 }
	global_store_dwordx4 v[172:173], v[188:191], off offset:32
	ds_read_b128 v[184:187], v175
	v_bfe_u32 v176, v90, 16, 1
	v_add3_u32 v176, v90, v176, s39
	v_bfe_u32 v177, v91, 16, 1
	v_add3_u32 v177, v91, v177, s39
	v_bfe_u32 v178, v92, 16, 1
	v_add3_u32 v178, v92, v178, s39
	v_bfe_u32 v179, v93, 16, 1
	v_add3_u32 v179, v93, v179, s39
	v_bfe_u32 v180, v82, 16, 1
	v_add3_u32 v180, v82, v180, s39
	v_bfe_u32 v181, v83, 16, 1
	v_add3_u32 v181, v83, v181, s39
	v_bfe_u32 v182, v84, 16, 1
	v_add3_u32 v182, v84, v182, s39
	v_bfe_u32 v183, v85, 16, 1
	v_add3_u32 v183, v85, v183, s39
	ds_write_b16_d16_hi v174, v176
	ds_write_b16_d16_hi v174, v177 offset:32
	ds_write_b16_d16_hi v174, v178 offset:64
	ds_write_b16_d16_hi v174, v179 offset:96
	ds_write_b16_d16_hi v174, v180 offset:128
	ds_write_b16_d16_hi v174, v181 offset:160
	ds_write_b16_d16_hi v174, v182 offset:192
	ds_write_b16_d16_hi v174, v183 offset:224
	s_waitcnt lgkmcnt(8)
	global_store_dwordx4 v[170:171], v[184:187], off offset:64
	ds_read_b128 v[188:191], v175
	v_bfe_u32 v176, v78, 16, 1
	v_add3_u32 v176, v78, v176, s39
	v_bfe_u32 v177, v79, 16, 1
	v_add3_u32 v177, v79, v177, s39
	v_bfe_u32 v178, v80, 16, 1
	v_add3_u32 v178, v80, v178, s39
	v_bfe_u32 v179, v81, 16, 1
	v_add3_u32 v179, v81, v179, s39
	v_bfe_u32 v180, v70, 16, 1
	v_add3_u32 v180, v70, v180, s39
	v_bfe_u32 v181, v71, 16, 1
	v_add3_u32 v181, v71, v181, s39
	v_bfe_u32 v182, v72, 16, 1
	v_add3_u32 v182, v72, v182, s39
	v_bfe_u32 v183, v73, 16, 1
	v_add3_u32 v183, v73, v183, s39
	ds_write_b16_d16_hi v174, v176
	ds_write_b16_d16_hi v174, v177 offset:32
	ds_write_b16_d16_hi v174, v178 offset:64
	ds_write_b16_d16_hi v174, v179 offset:96
	ds_write_b16_d16_hi v174, v180 offset:128
	ds_write_b16_d16_hi v174, v181 offset:160
	ds_write_b16_d16_hi v174, v182 offset:192
	ds_write_b16_d16_hi v174, v183 offset:224
	s_waitcnt lgkmcnt(8)
	global_store_dwordx4 v[172:173], v[188:191], off offset:64
	ds_read_b128 v[184:187], v175
	v_bfe_u32 v176, v74, 16, 1
	v_add3_u32 v176, v74, v176, s39
	v_bfe_u32 v177, v75, 16, 1
	v_add3_u32 v177, v75, v177, s39
	v_bfe_u32 v178, v76, 16, 1
	v_add3_u32 v178, v76, v178, s39
	v_bfe_u32 v179, v77, 16, 1
	v_add3_u32 v179, v77, v179, s39
	v_bfe_u32 v180, v66, 16, 1
	v_add3_u32 v180, v66, v180, s39
	v_bfe_u32 v181, v67, 16, 1
	v_add3_u32 v181, v67, v181, s39
	v_bfe_u32 v182, v68, 16, 1
	v_add3_u32 v182, v68, v182, s39
	v_bfe_u32 v183, v69, 16, 1
	v_add3_u32 v183, v69, v183, s39
	ds_write_b16_d16_hi v174, v176
	ds_write_b16_d16_hi v174, v177 offset:32
	ds_write_b16_d16_hi v174, v178 offset:64
	ds_write_b16_d16_hi v174, v179 offset:96
	ds_write_b16_d16_hi v174, v180 offset:128
	ds_write_b16_d16_hi v174, v181 offset:160
	ds_write_b16_d16_hi v174, v182 offset:192
	ds_write_b16_d16_hi v174, v183 offset:224
	s_waitcnt lgkmcnt(8)
	global_store_dwordx4 v[170:171], v[184:187], off offset:96
	ds_read_b128 v[188:191], v175
	v_bfe_u32 v176, v62, 16, 1
	v_add3_u32 v176, v62, v176, s39
	v_bfe_u32 v177, v63, 16, 1
	v_add3_u32 v177, v63, v177, s39
	v_bfe_u32 v178, v64, 16, 1
	v_add3_u32 v178, v64, v178, s39
	v_bfe_u32 v179, v65, 16, 1
	v_add3_u32 v179, v65, v179, s39
	v_bfe_u32 v180, v54, 16, 1
	v_add3_u32 v180, v54, v180, s39
	v_bfe_u32 v181, v55, 16, 1
	v_add3_u32 v181, v55, v181, s39
	v_bfe_u32 v182, v56, 16, 1
	v_add3_u32 v182, v56, v182, s39
	v_bfe_u32 v183, v57, 16, 1
	v_add3_u32 v183, v57, v183, s39
	ds_write_b16_d16_hi v174, v176
	ds_write_b16_d16_hi v174, v177 offset:32
	ds_write_b16_d16_hi v174, v178 offset:64
	ds_write_b16_d16_hi v174, v179 offset:96
	ds_write_b16_d16_hi v174, v180 offset:128
	ds_write_b16_d16_hi v174, v181 offset:160
	ds_write_b16_d16_hi v174, v182 offset:192
	ds_write_b16_d16_hi v174, v183 offset:224
	s_waitcnt lgkmcnt(8)
	global_store_dwordx4 v[172:173], v[188:191], off offset:96
	ds_read_b128 v[184:187], v175
	v_bfe_u32 v176, v58, 16, 1
	v_add3_u32 v176, v58, v176, s39
	v_bfe_u32 v177, v59, 16, 1
	v_add3_u32 v177, v59, v177, s39
	v_bfe_u32 v178, v60, 16, 1
	v_add3_u32 v178, v60, v178, s39
	v_bfe_u32 v179, v61, 16, 1
	v_add3_u32 v179, v61, v179, s39
	v_bfe_u32 v180, v50, 16, 1
	v_add3_u32 v180, v50, v180, s39
	v_bfe_u32 v181, v51, 16, 1
	v_add3_u32 v181, v51, v181, s39
	v_bfe_u32 v182, v52, 16, 1
	v_add3_u32 v182, v52, v182, s39
	v_bfe_u32 v183, v53, 16, 1
	v_add3_u32 v183, v53, v183, s39
	ds_write_b16_d16_hi v174, v176
	ds_write_b16_d16_hi v174, v177 offset:32
	ds_write_b16_d16_hi v174, v178 offset:64
	ds_write_b16_d16_hi v174, v179 offset:96
	ds_write_b16_d16_hi v174, v180 offset:128
	ds_write_b16_d16_hi v174, v181 offset:160
	ds_write_b16_d16_hi v174, v182 offset:192
	ds_write_b16_d16_hi v174, v183 offset:224
	s_waitcnt lgkmcnt(8)
	global_store_dwordx4 v[170:171], v[184:187], off offset:256
	ds_read_b128 v[188:191], v175
	v_bfe_u32 v176, v46, 16, 1
	v_add3_u32 v176, v46, v176, s39
	v_bfe_u32 v177, v47, 16, 1
	v_add3_u32 v177, v47, v177, s39
	v_bfe_u32 v178, v48, 16, 1
	v_add3_u32 v178, v48, v178, s39
	v_bfe_u32 v179, v49, 16, 1
	v_add3_u32 v179, v49, v179, s39
	v_bfe_u32 v180, v38, 16, 1
	v_add3_u32 v180, v38, v180, s39
	v_bfe_u32 v181, v39, 16, 1
	v_add3_u32 v181, v39, v181, s39
	v_bfe_u32 v182, v40, 16, 1
	v_add3_u32 v182, v40, v182, s39
	v_bfe_u32 v183, v41, 16, 1
	v_add3_u32 v183, v41, v183, s39
	ds_write_b16_d16_hi v174, v176
	ds_write_b16_d16_hi v174, v177 offset:32
	ds_write_b16_d16_hi v174, v178 offset:64
	ds_write_b16_d16_hi v174, v179 offset:96
	ds_write_b16_d16_hi v174, v180 offset:128
	ds_write_b16_d16_hi v174, v181 offset:160
	ds_write_b16_d16_hi v174, v182 offset:192
	ds_write_b16_d16_hi v174, v183 offset:224
	s_waitcnt lgkmcnt(8)
; __device__ __forceinline__ unsigned short f2bf1(float f) { unsigned u = __float_as_uint(f); return (unsigned short)((u + 0x7fffu + ((u >> 16) & 1u)) >> 16); }
;     __device__ __forceinline__ void operator()(const f32x4 (&acc)[2][2][4][2], const Unit& u, int wr, int wc, int fr, int fq) const {
;     ...
;             const int h = (pn - 8) >> 1, eb = ((pn - 8) & 1) * 256 + jb;
; #pragma unroll
;             for (int ai = 0; ai < 2; ++ai)
; #pragma unroll
;                 for (int m = 0; m < 4; ++m) {
;                     const int row = rowb + ai * HALF + m * 16, b = row >> 13, s = row & (SEQ_ - 1);
; #pragma unroll
;                     for (int bj = 0; bj < 2; ++bj)
; #pragma unroll
;                         for (int n = 0; n < 2; ++n)
; #pragma unroll
;                             for (int i = 0; i < 4; ++i) { const int e = eb + 128 * bj + 4 * n + i; VT[((size_t)((b * 4 + h) * 512 + e)) * SEQ_ + s] = f2bf1(acc[ai][bj][m][n][i]); }
;                 }
	global_store_dwordx4 v[172:173], v[188:191], off offset:256
	ds_read_b128 v[184:187], v175
	v_bfe_u32 v176, v42, 16, 1
	v_add3_u32 v176, v42, v176, s39
	v_bfe_u32 v177, v43, 16, 1
	v_add3_u32 v177, v43, v177, s39
	v_bfe_u32 v178, v44, 16, 1
	v_add3_u32 v178, v44, v178, s39
	v_bfe_u32 v179, v45, 16, 1
	v_add3_u32 v179, v45, v179, s39
	v_bfe_u32 v180, v34, 16, 1
	v_add3_u32 v180, v34, v180, s39
	v_bfe_u32 v181, v35, 16, 1
	v_add3_u32 v181, v35, v181, s39
	v_bfe_u32 v182, v36, 16, 1
	v_add3_u32 v182, v36, v182, s39
	v_bfe_u32 v183, v37, 16, 1
	v_add3_u32 v183, v37, v183, s39
	ds_write_b16_d16_hi v174, v176
	ds_write_b16_d16_hi v174, v177 offset:32
	ds_write_b16_d16_hi v174, v178 offset:64
	ds_write_b16_d16_hi v174, v179 offset:96
	ds_write_b16_d16_hi v174, v180 offset:128
	ds_write_b16_d16_hi v174, v181 offset:160
	ds_write_b16_d16_hi v174, v182 offset:192
	ds_write_b16_d16_hi v174, v183 offset:224
	s_waitcnt lgkmcnt(8)
	global_store_dwordx4 v[170:171], v[184:187], off offset:288
	ds_read_b128 v[188:191], v175
	v_bfe_u32 v176, v28, 16, 1
	v_add3_u32 v176, v28, v176, s39
	v_bfe_u32 v177, v29, 16, 1
	v_add3_u32 v177, v29, v177, s39
	v_bfe_u32 v178, v30, 16, 1
	v_add3_u32 v178, v30, v178, s39
	v_bfe_u32 v179, v31, 16, 1
	v_add3_u32 v179, v31, v179, s39
	v_bfe_u32 v180, v20, 16, 1
	v_add3_u32 v180, v20, v180, s39
	v_bfe_u32 v181, v21, 16, 1
	v_add3_u32 v181, v21, v181, s39
	v_bfe_u32 v182, v22, 16, 1
	v_add3_u32 v182, v22, v182, s39
	v_bfe_u32 v183, v23, 16, 1
	v_add3_u32 v183, v23, v183, s39
	ds_write_b16_d16_hi v174, v176
	ds_write_b16_d16_hi v174, v177 offset:32
	ds_write_b16_d16_hi v174, v178 offset:64
	ds_write_b16_d16_hi v174, v179 offset:96
	ds_write_b16_d16_hi v174, v180 offset:128
	ds_write_b16_d16_hi v174, v181 offset:160
	ds_write_b16_d16_hi v174, v182 offset:192
	ds_write_b16_d16_hi v174, v183 offset:224
	s_waitcnt lgkmcnt(8)
	global_store_dwordx4 v[172:173], v[188:191], off offset:288
	ds_read_b128 v[184:187], v175
	v_bfe_u32 v176, v24, 16, 1
	v_add3_u32 v176, v24, v176, s39
	v_bfe_u32 v177, v25, 16, 1
	v_add3_u32 v177, v25, v177, s39
	v_bfe_u32 v178, v26, 16, 1
	v_add3_u32 v178, v26, v178, s39
	v_bfe_u32 v179, v27, 16, 1
	v_add3_u32 v179, v27, v179, s39
	v_bfe_u32 v180, v16, 16, 1
	v_add3_u32 v180, v16, v180, s39
	v_bfe_u32 v181, v17, 16, 1
	v_add3_u32 v181, v17, v181, s39
	v_bfe_u32 v182, v18, 16, 1
	v_add3_u32 v182, v18, v182, s39
	v_bfe_u32 v183, v19, 16, 1
	v_add3_u32 v183, v19, v183, s39
	ds_write_b16_d16_hi v174, v176
	ds_write_b16_d16_hi v174, v177 offset:32
	ds_write_b16_d16_hi v174, v178 offset:64
	ds_write_b16_d16_hi v174, v179 offset:96
	ds_write_b16_d16_hi v174, v180 offset:128
	ds_write_b16_d16_hi v174, v181 offset:160
	ds_write_b16_d16_hi v174, v182 offset:192
	ds_write_b16_d16_hi v174, v183 offset:224
	s_waitcnt lgkmcnt(8)
	global_store_dwordx4 v[170:171], v[184:187], off offset:320
	ds_read_b128 v[188:191], v175
	v_bfe_u32 v176, v12, 16, 1
	v_add3_u32 v176, v12, v176, s39
	v_bfe_u32 v177, v13, 16, 1
	v_add3_u32 v177, v13, v177, s39
	v_bfe_u32 v178, v14, 16, 1
	v_add3_u32 v178, v14, v178, s39
	v_bfe_u32 v179, v15, 16, 1
	v_add3_u32 v179, v15, v179, s39
	v_bfe_u32 v180, v4, 16, 1
	v_add3_u32 v180, v4, v180, s39
	v_bfe_u32 v181, v5, 16, 1
	v_add3_u32 v181, v5, v181, s39
	v_bfe_u32 v182, v6, 16, 1
	v_add3_u32 v182, v6, v182, s39
	v_bfe_u32 v183, v7, 16, 1
	v_add3_u32 v183, v7, v183, s39
	ds_write_b16_d16_hi v174, v176
	ds_write_b16_d16_hi v174, v177 offset:32
	ds_write_b16_d16_hi v174, v178 offset:64
	ds_write_b16_d16_hi v174, v179 offset:96
	ds_write_b16_d16_hi v174, v180 offset:128
	ds_write_b16_d16_hi v174, v181 offset:160
	ds_write_b16_d16_hi v174, v182 offset:192
	ds_write_b16_d16_hi v174, v183 offset:224
	s_waitcnt lgkmcnt(8)
	global_store_dwordx4 v[172:173], v[188:191], off offset:320
	ds_read_b128 v[184:187], v175
	v_bfe_u32 v176, v8, 16, 1
	v_add3_u32 v176, v8, v176, s39
	v_bfe_u32 v177, v9, 16, 1
	v_add3_u32 v177, v9, v177, s39
	v_bfe_u32 v178, v10, 16, 1
	v_add3_u32 v178, v10, v178, s39
	v_bfe_u32 v179, v11, 16, 1
	v_add3_u32 v179, v11, v179, s39
	v_bfe_u32 v180, v0, 16, 1
	v_add3_u32 v180, v0, v180, s39
	v_bfe_u32 v181, v1, 16, 1
	v_add3_u32 v181, v1, v181, s39
	v_bfe_u32 v182, v2, 16, 1
	v_add3_u32 v182, v2, v182, s39
	v_bfe_u32 v183, v3, 16, 1
	v_add3_u32 v183, v3, v183, s39
	ds_write_b16_d16_hi v174, v176
	ds_write_b16_d16_hi v174, v177 offset:32
	ds_write_b16_d16_hi v174, v178 offset:64
	ds_write_b16_d16_hi v174, v179 offset:96
	ds_write_b16_d16_hi v174, v180 offset:128
	ds_write_b16_d16_hi v174, v181 offset:160
	ds_write_b16_d16_hi v174, v182 offset:192
	ds_write_b16_d16_hi v174, v183 offset:224
	s_waitcnt lgkmcnt(8)
	global_store_dwordx4 v[170:171], v[184:187], off offset:352
	ds_read_b128 v[188:191], v175
	s_waitcnt lgkmcnt(0)
	global_store_dwordx4 v[172:173], v[188:191], off offset:352
